# selected loop without per-MFMA-group priority flips
# speedup vs baseline: 1.0027x; 1.0027x over previous
.Lsb_wd_24:
	s_bfe_u32 s22, s17, 0x40000
	s_cmp_eq_u32 s22, 0
	s_cbranch_scc1 .Lsb_sg_25
	s_lshr_b32 s22, s17, 0
	v_lshrrev_b32_e64 v203, v165, s22
	v_and_b32_e32 v203, 1, v203
	v_cmp_eq_u32_e64 s[10:11], 1, v203
	s_nop 0
	v_mfma_f32_16x16x32_fp8_fp8 v[66:69], v[2:3], v[144:145], 0
	v_mfma_f32_16x16x32_fp8_fp8 v[70:73], v[6:7], v[144:145], 0
	v_mfma_f32_16x16x32_fp8_fp8 v[74:77], v[10:11], v[144:145], 0
	v_mfma_f32_16x16x32_fp8_fp8 v[78:81], v[14:15], v[144:145], 0
	v_mfma_f32_16x16x32_fp8_fp8 v[66:69], v[4:5], v[146:147], v[66:69]
	v_mfma_f32_16x16x32_fp8_fp8 v[70:73], v[8:9], v[146:147], v[70:73]
	v_mfma_f32_16x16x32_fp8_fp8 v[74:77], v[12:13], v[146:147], v[74:77]
	v_mfma_f32_16x16x32_fp8_fp8 v[78:81], v[16:17], v[146:147], v[78:81]
	s_nop 0
	v_cndmask_b32_e64 v204, v200, v158, s[10:11]
	s_cmp_eq_u32 s14, s48
	s_nop 1
	s_cbranch_scc1 .Lsb_dg_26

.Lsb_pv_29:
	v_add_f32_e32 v159, v159, v244
	s_nop 0
	v_mfma_f32_16x16x32_fp8_fp8 v[102:105], v[18:19], v[154:155], v[102:105]
	v_mfma_f32_16x16x32_fp8_fp8 v[106:109], v[22:23], v[154:155], v[106:109]
	v_mfma_f32_16x16x32_fp8_fp8 v[110:113], v[26:27], v[154:155], v[110:113]
	v_mfma_f32_16x16x32_fp8_fp8 v[114:117], v[30:31], v[154:155], v[114:117]
	v_mfma_f32_16x16x32_fp8_fp8 v[102:105], v[20:21], v[156:157], v[102:105]
	v_mfma_f32_16x16x32_fp8_fp8 v[106:109], v[24:25], v[156:157], v[106:109]
	v_mfma_f32_16x16x32_fp8_fp8 v[110:113], v[28:29], v[156:157], v[110:113]
	v_mfma_f32_16x16x32_fp8_fp8 v[114:117], v[32:33], v[156:157], v[114:117]
	s_nop 0
	s_branch .Lsb_ce_32

.Lsb_sl_28:
	s_nop 0
	v_mfma_f32_16x16x32_fp8_fp8 v[66:69], v[2:3], v[144:145], 0
	v_mfma_f32_16x16x32_fp8_fp8 v[70:73], v[6:7], v[144:145], 0
	v_mfma_f32_16x16x32_fp8_fp8 v[74:77], v[10:11], v[144:145], 0
	v_mfma_f32_16x16x32_fp8_fp8 v[78:81], v[14:15], v[144:145], 0
	v_mfma_f32_16x16x32_fp8_fp8 v[66:69], v[4:5], v[146:147], v[66:69]
	v_mfma_f32_16x16x32_fp8_fp8 v[70:73], v[8:9], v[146:147], v[70:73]
	v_mfma_f32_16x16x32_fp8_fp8 v[74:77], v[12:13], v[146:147], v[74:77]
	v_mfma_f32_16x16x32_fp8_fp8 v[78:81], v[16:17], v[146:147], v[78:81]
	s_nop 0
	s_cmp_lg_u32 s14, s48
	s_nop 7
	s_cbranch_scc1 .Lsb_sn_31
	v_sub_u32_e32 v244, v206, v187
	v_cmp_gt_i32_e32 vcc, 0, v244
	v_cmp_gt_i32_e64 s[22:23], 1, v244
	s_nop 0
	v_cndmask_b32_e32 v66, v66, v199, vcc
	v_cndmask_b32_e64 v67, v67, v199, s[22:23]
	v_cmp_gt_i32_e32 vcc, 2, v244
	v_cmp_gt_i32_e64 s[22:23], 3, v244
	s_nop 0
	v_cndmask_b32_e32 v68, v68, v199, vcc
	v_cndmask_b32_e64 v69, v69, v199, s[22:23]
	v_sub_u32_e32 v244, v206, v187
	v_subrev_u32_e32 v244, 16, v244
	v_cmp_gt_i32_e32 vcc, 0, v244
	v_cmp_gt_i32_e64 s[22:23], 1, v244
	s_nop 0
	v_cndmask_b32_e32 v70, v70, v199, vcc
	v_cndmask_b32_e64 v71, v71, v199, s[22:23]
	v_cmp_gt_i32_e32 vcc, 2, v244
	v_cmp_gt_i32_e64 s[22:23], 3, v244
	s_nop 0
	v_cndmask_b32_e32 v72, v72, v199, vcc
	v_cndmask_b32_e64 v73, v73, v199, s[22:23]
	v_sub_u32_e32 v244, v206, v187
	v_subrev_u32_e32 v244, 32, v244
	v_cmp_gt_i32_e32 vcc, 0, v244
	v_cmp_gt_i32_e64 s[22:23], 1, v244
	s_nop 0
	v_cndmask_b32_e32 v74, v74, v199, vcc
	v_cndmask_b32_e64 v75, v75, v199, s[22:23]
	v_cmp_gt_i32_e32 vcc, 2, v244
	v_cmp_gt_i32_e64 s[22:23], 3, v244
	s_nop 0
	v_cndmask_b32_e32 v76, v76, v199, vcc
	v_cndmask_b32_e64 v77, v77, v199, s[22:23]
	v_sub_u32_e32 v244, v206, v187
	v_subrev_u32_e32 v244, 48, v244
	v_cmp_gt_i32_e32 vcc, 0, v244
	v_cmp_gt_i32_e64 s[22:23], 1, v244
	s_nop 0
	v_cndmask_b32_e32 v78, v78, v199, vcc
	v_cndmask_b32_e64 v79, v79, v199, s[22:23]
	v_cmp_gt_i32_e32 vcc, 2, v244
	v_cmp_gt_i32_e64 s[22:23], 3, v244
	s_nop 0
	v_cndmask_b32_e32 v80, v80, v199, vcc
	v_cndmask_b32_e64 v81, v81, v199, s[22:23]

.Lsb_ce_32:
.Lsb_sg_25:
	s_bfe_u32 s22, s17, 0x40004
	s_cmp_eq_u32 s22, 0
	s_cbranch_scc1 .Lsb_sg_33
	s_lshr_b32 s22, s17, 4
	v_lshrrev_b32_e64 v203, v165, s22
	v_and_b32_e32 v203, 1, v203
	v_cmp_eq_u32_e64 s[10:11], 1, v203
	s_nop 0
	v_mfma_f32_16x16x32_fp8_fp8 v[66:69], v[2:3], v[150:151], 0
	v_mfma_f32_16x16x32_fp8_fp8 v[70:73], v[6:7], v[150:151], 0
	v_mfma_f32_16x16x32_fp8_fp8 v[74:77], v[10:11], v[150:151], 0
	v_mfma_f32_16x16x32_fp8_fp8 v[78:81], v[14:15], v[150:151], 0
	v_mfma_f32_16x16x32_fp8_fp8 v[66:69], v[4:5], v[152:153], v[66:69]
	v_mfma_f32_16x16x32_fp8_fp8 v[70:73], v[8:9], v[152:153], v[70:73]
	v_mfma_f32_16x16x32_fp8_fp8 v[74:77], v[12:13], v[152:153], v[74:77]
	v_mfma_f32_16x16x32_fp8_fp8 v[78:81], v[16:17], v[152:153], v[78:81]
	s_nop 0
	v_cndmask_b32_e64 v204, v200, v162, s[10:11]
	s_cmp_eq_u32 s14, s48
	s_nop 1
	s_cbranch_scc1 .Lsb_dg_34

.Lsb_pv_37:
	v_add_f32_e32 v163, v163, v244
	s_nop 0
	v_mfma_f32_16x16x32_fp8_fp8 v[118:121], v[18:19], v[154:155], v[118:121]
	v_mfma_f32_16x16x32_fp8_fp8 v[122:125], v[22:23], v[154:155], v[122:125]
	v_mfma_f32_16x16x32_fp8_fp8 v[136:139], v[26:27], v[154:155], v[136:139]
	v_mfma_f32_16x16x32_fp8_fp8 v[140:143], v[30:31], v[154:155], v[140:143]
	v_mfma_f32_16x16x32_fp8_fp8 v[118:121], v[20:21], v[156:157], v[118:121]
	v_mfma_f32_16x16x32_fp8_fp8 v[122:125], v[24:25], v[156:157], v[122:125]
	v_mfma_f32_16x16x32_fp8_fp8 v[136:139], v[28:29], v[156:157], v[136:139]
	v_mfma_f32_16x16x32_fp8_fp8 v[140:143], v[32:33], v[156:157], v[140:143]
	s_nop 0
	s_branch .Lsb_ce_40

.Lsb_sl_36:
	s_nop 0
	v_mfma_f32_16x16x32_fp8_fp8 v[66:69], v[2:3], v[150:151], 0
	v_mfma_f32_16x16x32_fp8_fp8 v[70:73], v[6:7], v[150:151], 0
	v_mfma_f32_16x16x32_fp8_fp8 v[74:77], v[10:11], v[150:151], 0
	v_mfma_f32_16x16x32_fp8_fp8 v[78:81], v[14:15], v[150:151], 0
	v_mfma_f32_16x16x32_fp8_fp8 v[66:69], v[4:5], v[152:153], v[66:69]
	v_mfma_f32_16x16x32_fp8_fp8 v[70:73], v[8:9], v[152:153], v[70:73]
	v_mfma_f32_16x16x32_fp8_fp8 v[74:77], v[12:13], v[152:153], v[74:77]
	v_mfma_f32_16x16x32_fp8_fp8 v[78:81], v[16:17], v[152:153], v[78:81]
	s_nop 0
	s_cmp_lg_u32 s14, s48
	s_nop 7
	s_cbranch_scc1 .Lsb_sn_39
	v_sub_u32_e32 v244, v206, v187
	v_subrev_u32_e32 v244, -4, v244
	v_cmp_gt_i32_e32 vcc, 0, v244
	v_cmp_gt_i32_e64 s[22:23], 1, v244
	s_nop 0
	v_cndmask_b32_e32 v66, v66, v199, vcc
	v_cndmask_b32_e64 v67, v67, v199, s[22:23]
	v_cmp_gt_i32_e32 vcc, 2, v244
	v_cmp_gt_i32_e64 s[22:23], 3, v244
	s_nop 0
	v_cndmask_b32_e32 v68, v68, v199, vcc
	v_cndmask_b32_e64 v69, v69, v199, s[22:23]
	v_sub_u32_e32 v244, v206, v187
	v_subrev_u32_e32 v244, 12, v244
	v_cmp_gt_i32_e32 vcc, 0, v244
	v_cmp_gt_i32_e64 s[22:23], 1, v244
	s_nop 0
	v_cndmask_b32_e32 v70, v70, v199, vcc
	v_cndmask_b32_e64 v71, v71, v199, s[22:23]
	v_cmp_gt_i32_e32 vcc, 2, v244
	v_cmp_gt_i32_e64 s[22:23], 3, v244
	s_nop 0
	v_cndmask_b32_e32 v72, v72, v199, vcc
	v_cndmask_b32_e64 v73, v73, v199, s[22:23]
	v_sub_u32_e32 v244, v206, v187
	v_subrev_u32_e32 v244, 28, v244
	v_cmp_gt_i32_e32 vcc, 0, v244
	v_cmp_gt_i32_e64 s[22:23], 1, v244
	s_nop 0
	v_cndmask_b32_e32 v74, v74, v199, vcc
	v_cndmask_b32_e64 v75, v75, v199, s[22:23]
	v_cmp_gt_i32_e32 vcc, 2, v244
	v_cmp_gt_i32_e64 s[22:23], 3, v244
	s_nop 0
	v_cndmask_b32_e32 v76, v76, v199, vcc
	v_cndmask_b32_e64 v77, v77, v199, s[22:23]
	v_sub_u32_e32 v244, v206, v187
	v_subrev_u32_e32 v244, 44, v244
	v_cmp_gt_i32_e32 vcc, 0, v244
	v_cmp_gt_i32_e64 s[22:23], 1, v244
	s_nop 0
	v_cndmask_b32_e32 v78, v78, v199, vcc
	v_cndmask_b32_e64 v79, v79, v199, s[22:23]
	v_cmp_gt_i32_e32 vcc, 2, v244
	v_cmp_gt_i32_e64 s[22:23], 3, v244
	s_nop 0
	v_cndmask_b32_e32 v80, v80, v199, vcc
	v_cndmask_b32_e64 v81, v81, v199, s[22:23]

.Lsb_wd_49:
	s_bfe_u32 s22, s17, 0x40000
	s_cmp_eq_u32 s22, 0
	s_cbranch_scc1 .Lsb_sg_50
	s_lshr_b32 s22, s17, 0
	v_lshrrev_b32_e64 v203, v165, s22
	v_and_b32_e32 v203, 1, v203
	v_cmp_eq_u32_e64 s[10:11], 1, v203
	s_nop 0
	v_mfma_f32_16x16x32_fp8_fp8 v[66:69], v[34:35], v[144:145], 0
	v_mfma_f32_16x16x32_fp8_fp8 v[70:73], v[38:39], v[144:145], 0
	v_mfma_f32_16x16x32_fp8_fp8 v[74:77], v[42:43], v[144:145], 0
	v_mfma_f32_16x16x32_fp8_fp8 v[78:81], v[46:47], v[144:145], 0
	v_mfma_f32_16x16x32_fp8_fp8 v[66:69], v[36:37], v[146:147], v[66:69]
	v_mfma_f32_16x16x32_fp8_fp8 v[70:73], v[40:41], v[146:147], v[70:73]
	v_mfma_f32_16x16x32_fp8_fp8 v[74:77], v[44:45], v[146:147], v[74:77]
	v_mfma_f32_16x16x32_fp8_fp8 v[78:81], v[48:49], v[146:147], v[78:81]
	s_nop 0
	v_cndmask_b32_e64 v204, v200, v158, s[10:11]
	s_cmp_eq_u32 s14, s48
	s_nop 1
	s_cbranch_scc1 .Lsb_dg_51

.Lsb_pv_54:
	v_add_f32_e32 v159, v159, v244
	s_nop 0
	v_mfma_f32_16x16x32_fp8_fp8 v[102:105], v[50:51], v[154:155], v[102:105]
	v_mfma_f32_16x16x32_fp8_fp8 v[106:109], v[54:55], v[154:155], v[106:109]
	v_mfma_f32_16x16x32_fp8_fp8 v[110:113], v[58:59], v[154:155], v[110:113]
	v_mfma_f32_16x16x32_fp8_fp8 v[114:117], v[62:63], v[154:155], v[114:117]
	v_mfma_f32_16x16x32_fp8_fp8 v[102:105], v[52:53], v[156:157], v[102:105]
	v_mfma_f32_16x16x32_fp8_fp8 v[106:109], v[56:57], v[156:157], v[106:109]
	v_mfma_f32_16x16x32_fp8_fp8 v[110:113], v[60:61], v[156:157], v[110:113]
	v_mfma_f32_16x16x32_fp8_fp8 v[114:117], v[64:65], v[156:157], v[114:117]
	s_nop 0
	s_branch .Lsb_ce_57

.Lsb_sl_53:
	s_nop 0
	v_mfma_f32_16x16x32_fp8_fp8 v[66:69], v[34:35], v[144:145], 0
	v_mfma_f32_16x16x32_fp8_fp8 v[70:73], v[38:39], v[144:145], 0
	v_mfma_f32_16x16x32_fp8_fp8 v[74:77], v[42:43], v[144:145], 0
	v_mfma_f32_16x16x32_fp8_fp8 v[78:81], v[46:47], v[144:145], 0
	v_mfma_f32_16x16x32_fp8_fp8 v[66:69], v[36:37], v[146:147], v[66:69]
	v_mfma_f32_16x16x32_fp8_fp8 v[70:73], v[40:41], v[146:147], v[70:73]
	v_mfma_f32_16x16x32_fp8_fp8 v[74:77], v[44:45], v[146:147], v[74:77]
	v_mfma_f32_16x16x32_fp8_fp8 v[78:81], v[48:49], v[146:147], v[78:81]
	s_nop 0
	s_cmp_lg_u32 s14, s48
	s_nop 7
	s_cbranch_scc1 .Lsb_sn_56
	v_sub_u32_e32 v244, v206, v187
	v_cmp_gt_i32_e32 vcc, 0, v244
	v_cmp_gt_i32_e64 s[22:23], 1, v244
	s_nop 0
	v_cndmask_b32_e32 v66, v66, v199, vcc
	v_cndmask_b32_e64 v67, v67, v199, s[22:23]
	v_cmp_gt_i32_e32 vcc, 2, v244
	v_cmp_gt_i32_e64 s[22:23], 3, v244
	s_nop 0
	v_cndmask_b32_e32 v68, v68, v199, vcc
	v_cndmask_b32_e64 v69, v69, v199, s[22:23]
	v_sub_u32_e32 v244, v206, v187
	v_subrev_u32_e32 v244, 16, v244
	v_cmp_gt_i32_e32 vcc, 0, v244
	v_cmp_gt_i32_e64 s[22:23], 1, v244
	s_nop 0
	v_cndmask_b32_e32 v70, v70, v199, vcc
	v_cndmask_b32_e64 v71, v71, v199, s[22:23]
	v_cmp_gt_i32_e32 vcc, 2, v244
	v_cmp_gt_i32_e64 s[22:23], 3, v244
	s_nop 0
	v_cndmask_b32_e32 v72, v72, v199, vcc
	v_cndmask_b32_e64 v73, v73, v199, s[22:23]
	v_sub_u32_e32 v244, v206, v187
	v_subrev_u32_e32 v244, 32, v244
	v_cmp_gt_i32_e32 vcc, 0, v244
	v_cmp_gt_i32_e64 s[22:23], 1, v244
	s_nop 0
	v_cndmask_b32_e32 v74, v74, v199, vcc
	v_cndmask_b32_e64 v75, v75, v199, s[22:23]
	v_cmp_gt_i32_e32 vcc, 2, v244
	v_cmp_gt_i32_e64 s[22:23], 3, v244
	s_nop 0
	v_cndmask_b32_e32 v76, v76, v199, vcc
	v_cndmask_b32_e64 v77, v77, v199, s[22:23]
	v_sub_u32_e32 v244, v206, v187
	v_subrev_u32_e32 v244, 48, v244
	v_cmp_gt_i32_e32 vcc, 0, v244
	v_cmp_gt_i32_e64 s[22:23], 1, v244
	s_nop 0
	v_cndmask_b32_e32 v78, v78, v199, vcc
	v_cndmask_b32_e64 v79, v79, v199, s[22:23]
	v_cmp_gt_i32_e32 vcc, 2, v244
	v_cmp_gt_i32_e64 s[22:23], 3, v244
	s_nop 0
	v_cndmask_b32_e32 v80, v80, v199, vcc
	v_cndmask_b32_e64 v81, v81, v199, s[22:23]

.Lsb_ce_57:
.Lsb_sg_50:
	s_bfe_u32 s22, s17, 0x40004
	s_cmp_eq_u32 s22, 0
	s_cbranch_scc1 .Lsb_sg_58
	s_lshr_b32 s22, s17, 4
	v_lshrrev_b32_e64 v203, v165, s22
	v_and_b32_e32 v203, 1, v203
	v_cmp_eq_u32_e64 s[10:11], 1, v203
	s_nop 0
	v_mfma_f32_16x16x32_fp8_fp8 v[66:69], v[34:35], v[150:151], 0
	v_mfma_f32_16x16x32_fp8_fp8 v[70:73], v[38:39], v[150:151], 0
	v_mfma_f32_16x16x32_fp8_fp8 v[74:77], v[42:43], v[150:151], 0
	v_mfma_f32_16x16x32_fp8_fp8 v[78:81], v[46:47], v[150:151], 0
	v_mfma_f32_16x16x32_fp8_fp8 v[66:69], v[36:37], v[152:153], v[66:69]
	v_mfma_f32_16x16x32_fp8_fp8 v[70:73], v[40:41], v[152:153], v[70:73]
	v_mfma_f32_16x16x32_fp8_fp8 v[74:77], v[44:45], v[152:153], v[74:77]
	v_mfma_f32_16x16x32_fp8_fp8 v[78:81], v[48:49], v[152:153], v[78:81]
	s_nop 0
	v_cndmask_b32_e64 v204, v200, v162, s[10:11]
	s_cmp_eq_u32 s14, s48
	s_nop 1
	s_cbranch_scc1 .Lsb_dg_59

.Lsb_pv_62:
	v_add_f32_e32 v163, v163, v244
	s_nop 0
	v_mfma_f32_16x16x32_fp8_fp8 v[118:121], v[50:51], v[154:155], v[118:121]
	v_mfma_f32_16x16x32_fp8_fp8 v[122:125], v[54:55], v[154:155], v[122:125]
	v_mfma_f32_16x16x32_fp8_fp8 v[136:139], v[58:59], v[154:155], v[136:139]
	v_mfma_f32_16x16x32_fp8_fp8 v[140:143], v[62:63], v[154:155], v[140:143]
	v_mfma_f32_16x16x32_fp8_fp8 v[118:121], v[52:53], v[156:157], v[118:121]
	v_mfma_f32_16x16x32_fp8_fp8 v[122:125], v[56:57], v[156:157], v[122:125]
	v_mfma_f32_16x16x32_fp8_fp8 v[136:139], v[60:61], v[156:157], v[136:139]
	v_mfma_f32_16x16x32_fp8_fp8 v[140:143], v[64:65], v[156:157], v[140:143]
	s_nop 0
	s_branch .Lsb_ce_65

.Lsb_sl_61:
	s_nop 0
	v_mfma_f32_16x16x32_fp8_fp8 v[66:69], v[34:35], v[150:151], 0
	v_mfma_f32_16x16x32_fp8_fp8 v[70:73], v[38:39], v[150:151], 0
	v_mfma_f32_16x16x32_fp8_fp8 v[74:77], v[42:43], v[150:151], 0
	v_mfma_f32_16x16x32_fp8_fp8 v[78:81], v[46:47], v[150:151], 0
	v_mfma_f32_16x16x32_fp8_fp8 v[66:69], v[36:37], v[152:153], v[66:69]
	v_mfma_f32_16x16x32_fp8_fp8 v[70:73], v[40:41], v[152:153], v[70:73]
	v_mfma_f32_16x16x32_fp8_fp8 v[74:77], v[44:45], v[152:153], v[74:77]
	v_mfma_f32_16x16x32_fp8_fp8 v[78:81], v[48:49], v[152:153], v[78:81]
	s_nop 0
	s_cmp_lg_u32 s14, s48
	s_nop 7
	s_cbranch_scc1 .Lsb_sn_64
	v_sub_u32_e32 v244, v206, v187
	v_subrev_u32_e32 v244, -4, v244
	v_cmp_gt_i32_e32 vcc, 0, v244
	v_cmp_gt_i32_e64 s[22:23], 1, v244
	s_nop 0
	v_cndmask_b32_e32 v66, v66, v199, vcc
	v_cndmask_b32_e64 v67, v67, v199, s[22:23]
	v_cmp_gt_i32_e32 vcc, 2, v244
	v_cmp_gt_i32_e64 s[22:23], 3, v244
	s_nop 0
	v_cndmask_b32_e32 v68, v68, v199, vcc
	v_cndmask_b32_e64 v69, v69, v199, s[22:23]
	v_sub_u32_e32 v244, v206, v187
	v_subrev_u32_e32 v244, 12, v244
	v_cmp_gt_i32_e32 vcc, 0, v244
	v_cmp_gt_i32_e64 s[22:23], 1, v244
	s_nop 0
	v_cndmask_b32_e32 v70, v70, v199, vcc
	v_cndmask_b32_e64 v71, v71, v199, s[22:23]
	v_cmp_gt_i32_e32 vcc, 2, v244
	v_cmp_gt_i32_e64 s[22:23], 3, v244
	s_nop 0
	v_cndmask_b32_e32 v72, v72, v199, vcc
	v_cndmask_b32_e64 v73, v73, v199, s[22:23]
	v_sub_u32_e32 v244, v206, v187
	v_subrev_u32_e32 v244, 28, v244
	v_cmp_gt_i32_e32 vcc, 0, v244
	v_cmp_gt_i32_e64 s[22:23], 1, v244
	s_nop 0
	v_cndmask_b32_e32 v74, v74, v199, vcc
	v_cndmask_b32_e64 v75, v75, v199, s[22:23]
	v_cmp_gt_i32_e32 vcc, 2, v244
	v_cmp_gt_i32_e64 s[22:23], 3, v244
	s_nop 0
	v_cndmask_b32_e32 v76, v76, v199, vcc
	v_cndmask_b32_e64 v77, v77, v199, s[22:23]
	v_sub_u32_e32 v244, v206, v187
	v_subrev_u32_e32 v244, 44, v244
	v_cmp_gt_i32_e32 vcc, 0, v244
	v_cmp_gt_i32_e64 s[22:23], 1, v244
	s_nop 0
	v_cndmask_b32_e32 v78, v78, v199, vcc
	v_cndmask_b32_e64 v79, v79, v199, s[22:23]
	v_cmp_gt_i32_e32 vcc, 2, v244
	v_cmp_gt_i32_e64 s[22:23], 3, v244
	s_nop 0
	v_cndmask_b32_e32 v80, v80, v199, vcc
	v_cndmask_b32_e64 v81, v81, v199, s[22:23]

.Lsb_wd_74:
	s_bfe_u32 s22, s17, 0x40000
	s_cmp_eq_u32 s22, 0
	s_cbranch_scc1 .Lsb_sg_75
	s_lshr_b32 s22, s17, 0
	v_lshrrev_b32_e64 v203, v165, s22
	v_and_b32_e32 v203, 1, v203
	v_cmp_eq_u32_e64 s[10:11], 1, v203
	s_nop 0
	v_mfma_f32_16x16x32_fp8_fp8 v[66:69], v[212:213], v[144:145], 0
	v_mfma_f32_16x16x32_fp8_fp8 v[70:73], v[216:217], v[144:145], 0
	v_mfma_f32_16x16x32_fp8_fp8 v[74:77], v[220:221], v[144:145], 0
	v_mfma_f32_16x16x32_fp8_fp8 v[78:81], v[224:225], v[144:145], 0
	v_mfma_f32_16x16x32_fp8_fp8 v[66:69], v[214:215], v[146:147], v[66:69]
	v_mfma_f32_16x16x32_fp8_fp8 v[70:73], v[218:219], v[146:147], v[70:73]
	v_mfma_f32_16x16x32_fp8_fp8 v[74:77], v[222:223], v[146:147], v[74:77]
	v_mfma_f32_16x16x32_fp8_fp8 v[78:81], v[226:227], v[146:147], v[78:81]
	s_nop 0
	v_cndmask_b32_e64 v204, v200, v158, s[10:11]
	s_cmp_eq_u32 s14, s48
	s_nop 1
	s_cbranch_scc1 .Lsb_dg_76

.Lsb_pv_79:
	v_add_f32_e32 v159, v159, v244
	s_nop 0
	v_mfma_f32_16x16x32_fp8_fp8 v[102:105], v[228:229], v[154:155], v[102:105]
	v_mfma_f32_16x16x32_fp8_fp8 v[106:109], v[232:233], v[154:155], v[106:109]
	v_mfma_f32_16x16x32_fp8_fp8 v[110:113], v[236:237], v[154:155], v[110:113]
	v_mfma_f32_16x16x32_fp8_fp8 v[114:117], v[240:241], v[154:155], v[114:117]
	v_mfma_f32_16x16x32_fp8_fp8 v[102:105], v[230:231], v[156:157], v[102:105]
	v_mfma_f32_16x16x32_fp8_fp8 v[106:109], v[234:235], v[156:157], v[106:109]
	v_mfma_f32_16x16x32_fp8_fp8 v[110:113], v[238:239], v[156:157], v[110:113]
	v_mfma_f32_16x16x32_fp8_fp8 v[114:117], v[242:243], v[156:157], v[114:117]
	s_nop 0
	s_branch .Lsb_ce_82

.Lsb_sl_78:
	s_nop 0
	v_mfma_f32_16x16x32_fp8_fp8 v[66:69], v[212:213], v[144:145], 0
	v_mfma_f32_16x16x32_fp8_fp8 v[70:73], v[216:217], v[144:145], 0
	v_mfma_f32_16x16x32_fp8_fp8 v[74:77], v[220:221], v[144:145], 0
	v_mfma_f32_16x16x32_fp8_fp8 v[78:81], v[224:225], v[144:145], 0
	v_mfma_f32_16x16x32_fp8_fp8 v[66:69], v[214:215], v[146:147], v[66:69]
	v_mfma_f32_16x16x32_fp8_fp8 v[70:73], v[218:219], v[146:147], v[70:73]
	v_mfma_f32_16x16x32_fp8_fp8 v[74:77], v[222:223], v[146:147], v[74:77]
	v_mfma_f32_16x16x32_fp8_fp8 v[78:81], v[226:227], v[146:147], v[78:81]
	s_nop 0
	s_cmp_lg_u32 s14, s48
	s_nop 7
	s_cbranch_scc1 .Lsb_sn_81
	v_sub_u32_e32 v244, v206, v187
	v_cmp_gt_i32_e32 vcc, 0, v244
	v_cmp_gt_i32_e64 s[22:23], 1, v244
	s_nop 0
	v_cndmask_b32_e32 v66, v66, v199, vcc
	v_cndmask_b32_e64 v67, v67, v199, s[22:23]
	v_cmp_gt_i32_e32 vcc, 2, v244
	v_cmp_gt_i32_e64 s[22:23], 3, v244
	s_nop 0
	v_cndmask_b32_e32 v68, v68, v199, vcc
	v_cndmask_b32_e64 v69, v69, v199, s[22:23]
	v_sub_u32_e32 v244, v206, v187
	v_subrev_u32_e32 v244, 16, v244
	v_cmp_gt_i32_e32 vcc, 0, v244
	v_cmp_gt_i32_e64 s[22:23], 1, v244
	s_nop 0
	v_cndmask_b32_e32 v70, v70, v199, vcc
	v_cndmask_b32_e64 v71, v71, v199, s[22:23]
	v_cmp_gt_i32_e32 vcc, 2, v244
	v_cmp_gt_i32_e64 s[22:23], 3, v244
	s_nop 0
	v_cndmask_b32_e32 v72, v72, v199, vcc
	v_cndmask_b32_e64 v73, v73, v199, s[22:23]
	v_sub_u32_e32 v244, v206, v187
	v_subrev_u32_e32 v244, 32, v244
	v_cmp_gt_i32_e32 vcc, 0, v244
	v_cmp_gt_i32_e64 s[22:23], 1, v244
	s_nop 0
	v_cndmask_b32_e32 v74, v74, v199, vcc
	v_cndmask_b32_e64 v75, v75, v199, s[22:23]
	v_cmp_gt_i32_e32 vcc, 2, v244
	v_cmp_gt_i32_e64 s[22:23], 3, v244
	s_nop 0
	v_cndmask_b32_e32 v76, v76, v199, vcc
	v_cndmask_b32_e64 v77, v77, v199, s[22:23]
	v_sub_u32_e32 v244, v206, v187
	v_subrev_u32_e32 v244, 48, v244
	v_cmp_gt_i32_e32 vcc, 0, v244
	v_cmp_gt_i32_e64 s[22:23], 1, v244
	s_nop 0
	v_cndmask_b32_e32 v78, v78, v199, vcc
	v_cndmask_b32_e64 v79, v79, v199, s[22:23]
	v_cmp_gt_i32_e32 vcc, 2, v244
	v_cmp_gt_i32_e64 s[22:23], 3, v244
	s_nop 0
	v_cndmask_b32_e32 v80, v80, v199, vcc
	v_cndmask_b32_e64 v81, v81, v199, s[22:23]

.Lsb_ce_82:
.Lsb_sg_75:
	s_bfe_u32 s22, s17, 0x40004
	s_cmp_eq_u32 s22, 0
	s_cbranch_scc1 .Lsb_sg_83
	s_lshr_b32 s22, s17, 4
	v_lshrrev_b32_e64 v203, v165, s22
	v_and_b32_e32 v203, 1, v203
	v_cmp_eq_u32_e64 s[10:11], 1, v203
	s_nop 0
	v_mfma_f32_16x16x32_fp8_fp8 v[66:69], v[212:213], v[150:151], 0
	v_mfma_f32_16x16x32_fp8_fp8 v[70:73], v[216:217], v[150:151], 0
	v_mfma_f32_16x16x32_fp8_fp8 v[74:77], v[220:221], v[150:151], 0
	v_mfma_f32_16x16x32_fp8_fp8 v[78:81], v[224:225], v[150:151], 0
	v_mfma_f32_16x16x32_fp8_fp8 v[66:69], v[214:215], v[152:153], v[66:69]
	v_mfma_f32_16x16x32_fp8_fp8 v[70:73], v[218:219], v[152:153], v[70:73]
	v_mfma_f32_16x16x32_fp8_fp8 v[74:77], v[222:223], v[152:153], v[74:77]
	v_mfma_f32_16x16x32_fp8_fp8 v[78:81], v[226:227], v[152:153], v[78:81]
	s_nop 0
	v_cndmask_b32_e64 v204, v200, v162, s[10:11]
	s_cmp_eq_u32 s14, s48
	s_nop 1
	s_cbranch_scc1 .Lsb_dg_84

.Lsb_pv_87:
	v_add_f32_e32 v163, v163, v244
	s_nop 0
	v_mfma_f32_16x16x32_fp8_fp8 v[118:121], v[228:229], v[154:155], v[118:121]
	v_mfma_f32_16x16x32_fp8_fp8 v[122:125], v[232:233], v[154:155], v[122:125]
	v_mfma_f32_16x16x32_fp8_fp8 v[136:139], v[236:237], v[154:155], v[136:139]
	v_mfma_f32_16x16x32_fp8_fp8 v[140:143], v[240:241], v[154:155], v[140:143]
	v_mfma_f32_16x16x32_fp8_fp8 v[118:121], v[230:231], v[156:157], v[118:121]
	v_mfma_f32_16x16x32_fp8_fp8 v[122:125], v[234:235], v[156:157], v[122:125]
	v_mfma_f32_16x16x32_fp8_fp8 v[136:139], v[238:239], v[156:157], v[136:139]
	v_mfma_f32_16x16x32_fp8_fp8 v[140:143], v[242:243], v[156:157], v[140:143]
	s_nop 0
	s_branch .Lsb_ce_90

.Lsb_sl_86:
	s_nop 0
	v_mfma_f32_16x16x32_fp8_fp8 v[66:69], v[212:213], v[150:151], 0
	v_mfma_f32_16x16x32_fp8_fp8 v[70:73], v[216:217], v[150:151], 0
	v_mfma_f32_16x16x32_fp8_fp8 v[74:77], v[220:221], v[150:151], 0
	v_mfma_f32_16x16x32_fp8_fp8 v[78:81], v[224:225], v[150:151], 0
	v_mfma_f32_16x16x32_fp8_fp8 v[66:69], v[214:215], v[152:153], v[66:69]
	v_mfma_f32_16x16x32_fp8_fp8 v[70:73], v[218:219], v[152:153], v[70:73]
	v_mfma_f32_16x16x32_fp8_fp8 v[74:77], v[222:223], v[152:153], v[74:77]
	v_mfma_f32_16x16x32_fp8_fp8 v[78:81], v[226:227], v[152:153], v[78:81]
	s_nop 0
	s_cmp_lg_u32 s14, s48
	s_nop 7
	s_cbranch_scc1 .Lsb_sn_89
	v_sub_u32_e32 v244, v206, v187
	v_subrev_u32_e32 v244, -4, v244
	v_cmp_gt_i32_e32 vcc, 0, v244
	v_cmp_gt_i32_e64 s[22:23], 1, v244
	s_nop 0
	v_cndmask_b32_e32 v66, v66, v199, vcc
	v_cndmask_b32_e64 v67, v67, v199, s[22:23]
	v_cmp_gt_i32_e32 vcc, 2, v244
	v_cmp_gt_i32_e64 s[22:23], 3, v244
	s_nop 0
	v_cndmask_b32_e32 v68, v68, v199, vcc
	v_cndmask_b32_e64 v69, v69, v199, s[22:23]
	v_sub_u32_e32 v244, v206, v187
	v_subrev_u32_e32 v244, 12, v244
	v_cmp_gt_i32_e32 vcc, 0, v244
	v_cmp_gt_i32_e64 s[22:23], 1, v244
	s_nop 0
	v_cndmask_b32_e32 v70, v70, v199, vcc
	v_cndmask_b32_e64 v71, v71, v199, s[22:23]
	v_cmp_gt_i32_e32 vcc, 2, v244
	v_cmp_gt_i32_e64 s[22:23], 3, v244
	s_nop 0
	v_cndmask_b32_e32 v72, v72, v199, vcc
	v_cndmask_b32_e64 v73, v73, v199, s[22:23]
	v_sub_u32_e32 v244, v206, v187
	v_subrev_u32_e32 v244, 28, v244
	v_cmp_gt_i32_e32 vcc, 0, v244
	v_cmp_gt_i32_e64 s[22:23], 1, v244
	s_nop 0
	v_cndmask_b32_e32 v74, v74, v199, vcc
	v_cndmask_b32_e64 v75, v75, v199, s[22:23]
	v_cmp_gt_i32_e32 vcc, 2, v244
	v_cmp_gt_i32_e64 s[22:23], 3, v244
	s_nop 0
	v_cndmask_b32_e32 v76, v76, v199, vcc
	v_cndmask_b32_e64 v77, v77, v199, s[22:23]
	v_sub_u32_e32 v244, v206, v187
	v_subrev_u32_e32 v244, 44, v244
	v_cmp_gt_i32_e32 vcc, 0, v244
	v_cmp_gt_i32_e64 s[22:23], 1, v244
	s_nop 0
	v_cndmask_b32_e32 v78, v78, v199, vcc
	v_cndmask_b32_e64 v79, v79, v199, s[22:23]
	v_cmp_gt_i32_e32 vcc, 2, v244
	v_cmp_gt_i32_e64 s[22:23], 3, v244
	s_nop 0
	v_cndmask_b32_e32 v80, v80, v199, vcc
	v_cndmask_b32_e64 v81, v81, v199, s[22:23]
